# one static s_setprio 1 for waves 0-3 (leading group) at kernel entry, all other s_setprio deleted
# speedup vs baseline: 1.0022x; 1.0022x over previous
; #define LAS __attribute__((address_space(3)))
; __global__ void __launch_bounds__(NTHREADS, 2) fwd_kernel(Args args_v) {
;     ...
;     const int wave_s = __builtin_amdgcn_readfirstlane((int)threadIdx.x >> 6);
;     volatile LAS unsigned* MISC = (volatile LAS unsigned*)(ldsp + MISC_OFF);
;     for (int u = threadIdx.x; u < (LDS_BYTES - LDSCTL_OFF) / 4; u += NTHREADS) ((LAS unsigned*)(ldsp + LDSCTL_OFF))[u] = 0u;
_Z10fwd_kernel4Args:
	v_lshl_add_u32 v1, v0, 2, 0
	v_add_u32_e32 v1, 0x20000, v1
	v_mov_b32_e32 v2, 0
	v_readfirstlane_b32 s93, v0
	s_nop 3
	s_cmp_lt_u32 s93, 0x100
	s_cbranch_scc0 .Lstatic_prio_done
	s_setprio 1
